# RG-LRU phase: one static s_setprio 1 for waves 4-7 (static priority raise for the younger wave half)
# speedup vs baseline: 1.0097x; 1.0008x over previous
; __device__ __forceinline__ void lru_phase(const Ptrs& P, LAS unsigned char* lds, int G, int wave, int lane, int tid) {
;     ...
;       if (tid < 160) pd[tid] = ps[tid]; }
;     __syncthreads();
;     v2u raw[10][4];
;     ...
;     if ((int)blockIdx.x < 64 * NCHUNK) LRU_LOAD_RAW((int)blockIdx.x);
.LBB0_295:
	s_or_b64 exec, exec, s[2:3]
	s_bitcmp1_b32 s63, 2
	s_cbranch_scc0 .Lp2_prio_done
	s_setprio 1
.Lp2_prio_done:
	s_cmpk_gt_i32 s33, 0x3ff
	s_waitcnt lgkmcnt(0)
	s_barrier
	s_cbranch_scc1 .LBB0_326
	s_add_u32 s10, s54, 0x3800000
	s_addc_u32 s11, s55, 0
	s_lshl_b32 s2, s33, 2
	s_and_b32 s2, s2, 0xffffff00
	s_lshl_b32 s26, s63, 5
	v_and_b32_e32 v185, 31, v184
	s_add_i32 s2, s26, s2
	v_add_u32_e32 v4, -3, v185
	s_add_u32 s12, s54, 0x1780000
	v_add_u32_e32 v5, s2, v4
	s_addc_u32 s13, s55, 0
	s_and_b32 s4, s68, 0x180
	v_and_b32_e32 v187, 32, v184
	v_mov_b32_e32 v3, 0
	v_cmp_lt_i32_e32 vcc, -1, v5
	v_mov_b64_e32 v[0:1], s[12:13]
	s_and_saveexec_b64 s[2:3], vcc
	v_lshrrev_b32_e32 v0, 5, v5
	v_add_u32_e32 v0, s4, v0
	v_lshl_or_b32 v0, v0, 4, s6
	v_mul_lo_u32 v2, v0, 10
	v_lshlrev_b64 v[0:1], 6, v[2:3]
	v_and_or_b32 v0, v4, 31, v0
	v_or_b32_e32 v0, v0, v187
	v_lshl_add_u64 v[0:1], v[0:1], 3, s[10:11]
	s_or_b64 exec, exec, s[2:3]
	global_load_dwordx2 v[40:41], v[0:1], off offset:1024
	global_load_dwordx2 v[42:43], v[0:1], off offset:1536
	global_load_dwordx2 v[76:77], v[0:1], off offset:2048
	global_load_dwordx2 v[78:79], v[0:1], off offset:2560
	global_load_dwordx2 v[112:113], v[0:1], off offset:3072
	global_load_dwordx2 v[28:29], v[0:1], off offset:3584
	v_add_co_u32_e32 v2, vcc, 0x1000, v0
	s_nop 1
	v_addc_co_u32_e32 v3, vcc, 0, v1, vcc
	global_load_dwordx2 v[36:37], v[0:1], off
	global_load_dwordx2 v[38:39], v[0:1], off offset:512
	global_load_dwordx2 v[20:21], v[2:3], off
	global_load_dwordx2 v[16:17], v[2:3], off offset:512
	v_cmp_lt_i32_e32 vcc, -2, v5
	v_mov_b64_e32 v[0:1], s[12:13]
	s_and_saveexec_b64 s[2:3], vcc
	s_cbranch_execz .LBB0_300
	v_add_u32_e32 v2, 1, v5
	v_lshrrev_b32_e32 v0, 5, v2
	v_add_u32_e32 v0, s4, v0
	v_lshl_or_b32 v0, v0, 4, s6
	v_mul_lo_u32 v0, v0, 10
	v_mov_b32_e32 v1, 0
	v_lshlrev_b64 v[0:1], 6, v[0:1]
	v_and_or_b32 v0, v2, 31, v0
	v_or_b32_e32 v0, v0, v187
	v_lshl_add_u64 v[0:1], v[0:1], 3, s[10:11]

; __device__ __forceinline__ unsigned xb_add(unsigned* p, unsigned v) { return __hip_atomic_fetch_add(p, v, __ATOMIC_RELAXED, __HIP_MEMORY_SCOPE_AGENT); }
; __device__ __forceinline__ void xcd_barrier(const XcdBarrier& b) {
;     asm volatile("s_waitcnt vmcnt(0)" ::: "memory");
;     __syncthreads();
;     if (threadIdx.x == 0) {
;         unsigned* bar = b.bar;
;         __builtin_amdgcn_s_waitcnt(0);
;         unsigned nloc = b.st[0], nx = b.st[1];
;         if (nloc == 0u) { xcd_barrier_complete(bar, b.x, nloc, nx); b.st[0] = nloc; b.st[1] = nx; }
;         const unsigned old = xb_add(&bar[XB_XSUB(b.x)], 1u);
; __global__ void __launch_bounds__(NT, 2) trunk_fwd(Args args) {
;     ...
;     if (IN(2) && IN(4)) xcd_barrier(bar);
.LBB0_327:
	s_setprio 0
	s_cmp_gt_i32 s57, 4
	s_cselect_b64 s[2:3], -1, 0
	s_and_b64 s[4:5], s[8:9], s[2:3]
	s_andn2_b64 vcc, exec, s[4:5]
	s_cbranch_vccnz .LBB0_381
	s_waitcnt vmcnt(0)
	s_barrier
	s_and_saveexec_b64 s[4:5], s[0:1]
	s_cbranch_execz .LBB0_380
	s_add_i32 s6, 0, 0x20000
	v_mov_b32_e32 v0, s6
	s_waitcnt vmcnt(0) expcnt(0) lgkmcnt(0)
	ds_read_b32 v2, v0
	s_add_i32 s6, 0, 0x20004
	v_mov_b32_e32 v0, s6
	ds_read_b32 v0, v0
	s_waitcnt lgkmcnt(1)
	v_cmp_ne_u32_e32 vcc, 0, v2
	s_cbranch_vccnz .LBB0_344
	s_add_u32 s6, s54, 0x1000
	s_addc_u32 s7, s55, 0
	s_add_u32 s8, s54, 0x1100
	s_addc_u32 s9, s55, 0
	s_add_u32 s10, s54, 0x1200
	s_addc_u32 s11, s55, 0
	s_mul_i32 s20, s65, s61
	s_add_u32 s12, s54, 0x1300
	s_mul_i32 s20, s20, s64
	s_addc_u32 s13, s55, 0
	s_mov_b32 s21, 1
	v_mov_b32_e32 v16, 0
	s_branch .LBB0_332
